# P10 conv loop: dropped the vmcnt(0) at the loop head (previous task's stores no longer drained before the next task's loads; counted waits below unchanged)
# baseline (speedup 1.0000x reference)
.LBB0_1009:
	v_mul_hi_i32 v2, v1, s31
	v_lshrrev_b32_e32 v3, 31, v2
	v_ashrrev_i32_e32 v2, 8, v2
	v_add_u32_e32 v2, v2, v3
	v_mul_i32_i24_e32 v3, 0x580, v2
	v_lshlrev_b32_e32 v3, 2, v3
	v_lshlrev_b32_e32 v90, 3, v2
	v_and_b32_e32 v12, 0x1ff, v2
	v_sub_u32_e32 v36, v82, v3
	v_add_u32_e32 v2, -2, v90
	v_cmp_ne_u32_e32 vcc, 0, v12
	v_ashrrev_i32_e32 v37, 31, v36
	v_lshlrev_b64 v[4:5], 1, v[36:37]
	v_cndmask_b32_e32 v2, v90, v2, vcc
	v_mad_i64_i32 v[2:3], s[6:7], v2, s36, v[34:35]
	v_lshl_add_u64 v[2:3], v[2:3], 0, v[4:5]
	v_add_co_u32_e64 v6, s[6:7], s37, v2
	v_subbrev_co_u32_e32 v8, vcc, 0, v90, vcc
	s_nop 0
	v_addc_co_u32_e64 v7, s[6:7], 0, v3, s[6:7]
	v_mad_i64_i32 v[8:9], s[6:7], v8, s36, v[34:35]
	v_lshl_add_u64 v[8:9], v[8:9], 0, v[4:5]
	v_add_co_u32_e32 v10, vcc, s37, v8
	v_or_b32_e32 v89, 1, v90
	s_nop 0
	v_addc_co_u32_e32 v11, vcc, 0, v9, vcc
	global_load_dwordx2 v[62:63], v[2:3], off
	global_load_dwordx2 v[66:67], v[6:7], off offset:3072
	global_load_dwordx2 v[72:73], v[8:9], off
	global_load_dwordx2 v[76:77], v[10:11], off offset:3072
	v_mad_i64_i32 v[2:3], s[6:7], v90, s36, v[34:35]
	v_lshl_add_u64 v[2:3], v[2:3], 0, v[4:5]
	v_add_co_u32_e32 v6, vcc, s37, v2
	v_mad_i64_i32 v[8:9], s[6:7], v89, s36, v[34:35]
	s_nop 0
	v_addc_co_u32_e32 v7, vcc, 0, v3, vcc
	v_lshl_add_u64 v[8:9], v[8:9], 0, v[4:5]
	v_add_co_u32_e32 v10, vcc, s37, v8
	v_or_b32_e32 v88, 2, v90
	s_nop 0
	v_addc_co_u32_e32 v11, vcc, 0, v9, vcc
	global_load_dwordx2 v[80:81], v[2:3], off
	global_load_dwordx2 v[78:79], v[6:7], off offset:3072
	global_load_dwordx2 v[68:69], v[8:9], off
	global_load_dwordx2 v[64:65], v[10:11], off offset:3072
	v_mad_i64_i32 v[2:3], s[6:7], v88, s36, v[34:35]
	v_lshl_add_u64 v[2:3], v[2:3], 0, v[4:5]
	v_or_b32_e32 v87, 3, v90
	v_add_co_u32_e32 v6, vcc, s37, v2
	v_mad_i64_i32 v[8:9], s[6:7], v87, s36, v[34:35]
	s_nop 0
	v_addc_co_u32_e32 v7, vcc, 0, v3, vcc
	v_lshl_add_u64 v[8:9], v[8:9], 0, v[4:5]
	v_add_co_u32_e32 v10, vcc, s37, v8
	v_or_b32_e32 v86, 4, v90
	s_nop 0
	v_addc_co_u32_e32 v11, vcc, 0, v9, vcc
	global_load_dwordx2 v[60:61], v[2:3], off
	global_load_dwordx2 v[58:59], v[6:7], off offset:3072
	global_load_dwordx2 v[56:57], v[8:9], off
	global_load_dwordx2 v[54:55], v[10:11], off offset:3072
	v_mad_i64_i32 v[2:3], s[6:7], v86, s36, v[34:35]
	v_lshl_add_u64 v[2:3], v[2:3], 0, v[4:5]
	v_or_b32_e32 v85, 5, v90
	v_add_co_u32_e32 v6, vcc, s37, v2
	v_mad_i64_i32 v[8:9], s[6:7], v85, s36, v[34:35]
	s_nop 0
	v_addc_co_u32_e32 v7, vcc, 0, v3, vcc
	v_lshl_add_u64 v[8:9], v[8:9], 0, v[4:5]
	v_add_co_u32_e32 v10, vcc, s37, v8
	v_or_b32_e32 v84, 6, v90
	s_nop 0
	v_addc_co_u32_e32 v11, vcc, 0, v9, vcc
	global_load_dwordx2 v[52:53], v[2:3], off
	global_load_dwordx2 v[50:51], v[6:7], off offset:3072
	global_load_dwordx2 v[48:49], v[8:9], off
	global_load_dwordx2 v[46:47], v[10:11], off offset:3072
	v_mad_i64_i32 v[2:3], s[6:7], v84, s36, v[34:35]
	v_lshl_add_u64 v[2:3], v[2:3], 0, v[4:5]
	v_or_b32_e32 v83, 7, v90
	v_add_co_u32_e32 v6, vcc, s37, v2
	v_mad_i64_i32 v[8:9], s[6:7], v83, s36, v[34:35]
	s_nop 0
	v_addc_co_u32_e32 v7, vcc, 0, v3, vcc
	v_lshl_add_u64 v[4:5], v[8:9], 0, v[4:5]
	v_add_co_u32_e32 v8, vcc, 0x2000, v4
	s_nop 1
	v_addc_co_u32_e32 v9, vcc, 0, v5, vcc
	global_load_dwordx2 v[44:45], v[2:3], off
	global_load_dwordx2 v[42:43], v[6:7], off offset:3072
	global_load_dwordx2 v[40:41], v[4:5], off
	global_load_dwordx2 v[38:39], v[8:9], off offset:3072
	v_cmp_eq_u32_e32 vcc, 0, v12
	s_and_saveexec_b64 s[6:7], vcc
	s_cbranch_execz .LBB0_1008
	s_waitcnt vmcnt(19)
	v_mov_b64_e32 v[62:63], 0
	s_waitcnt vmcnt(17)
	v_mov_b64_e32 v[72:73], 0
	s_waitcnt vmcnt(16)
	v_mov_b64_e32 v[76:77], 0
	v_mov_b64_e32 v[66:67], 0
	s_branch .LBB0_1008
